# attention: the 36 relative-bias LDS reads of the score section issued together after QK^T (one wait) and folded with v_fmamk_f32 instead of 36 read-wait-fmac round trips
# baseline (speedup 1.0000x reference)
; __device__ __forceinline__ f32x4 mfma32(bf16x8 a, bf16x8 b, f32x4 c) { return __builtin_amdgcn_mfma_f32_16x16x32_bf16(a, b, c, 0, 0, 0); }
; __device__ __forceinline__ void attn_unit(const Ptrs& P, int l, int b, int gk, int n, unsigned char* lds, int tid, bool dost) {
;     ...
;         for (int kt = 0; kt < 9; ++kt) { const unsigned char* kp = lds + AT_KS + (16 * (qs + kt) + lc) * 144 + 16 * g;
;             const bf16x8 a0 = *(const bf16x8*)kp, a1 = *(const bf16x8*)(kp + 64);
;             f32x4 z = {0.f, 0.f, 0.f, 0.f}; z = mfma32(a0, q0, z); st[kt] = mfma32(a1, q1, z); }
;         { const unsigned char* kp = lds + AT_KM + lc * 144 + 16 * g; const bf16x8 a0 = *(const bf16x8*)kp, a1 = *(const bf16x8*)(kp + 64);
;             f32x4 z = {0.f, 0.f, 0.f, 0.f}; z = mfma32(a0, q0, z); st[9] = mfma32(a1, q1, z); }
;         float mx = sink;
; #pragma unroll
;         for (int kt = 0; kt < 9; ++kt)
; #pragma unroll
;             for (int r = 0; r < 4; ++r) { const int dist = 128 + lc - 16 * kt - 4 * g - r; const int j = 16 * (qs + kt) + 4 * g + r;
;                 const bool valid = (dist >= 0) && (dist < 128) && (n >= 1) && (n >= 2 || j >= 128);
;                 const float lg = valid ? (st[kt][r] * 0.125f + hb[w * 128 + (dist & 127)]) : NEGV; st[kt][r] = lg; mx = fmaxf(mx, lg); }
; #pragma unroll
;         for (int r = 0; r < 4; ++r) { const int dist = tq - (4 * g + r); const bool valid = dist >= 0; const int bk = (dist >= 0 && dist < 128) ? bkt[dist & 127] : 31;
;             const float lg = valid ? (st[9][r] * 0.125f + rb[bk * 16 + head]) : NEGV; st[9][r] = lg; mx = fmaxf(mx, lg); }
.LBB0_323:
	v_add_u32_e32 v22, 0, v118
	ds_read_b128 v[150:153], v22
	ds_read_b128 v[154:157], v22 offset:64
	ds_read_b128 v[158:161], v22 offset:2304
	ds_read_b128 v[162:165], v22 offset:2368
	ds_read_b128 v[166:169], v22 offset:4608
	ds_read_b128 v[170:173], v22 offset:4672
	ds_read_b128 v[174:177], v22 offset:6912
	ds_read_b128 v[178:181], v22 offset:6976
	ds_read_b128 v[182:185], v22 offset:9216
	ds_read_b128 v[186:189], v22 offset:9280
	ds_read_b128 v[190:193], v22 offset:11520
	ds_read_b128 v[196:199], v22 offset:11584
	ds_read_b128 v[200:203], v22 offset:13824
	s_nop 0
	ds_read_b128 v[204:207], v22 offset:13888
	s_waitcnt lgkmcnt(13)
	v_mfma_f32_16x16x32_bf16 v[42:45], v[150:153], v[38:41], 0
	s_waitcnt lgkmcnt(12)
	v_mfma_f32_16x16x32_bf16 v[78:81], v[154:157], v[70:73], v[42:45]
	s_nop 5
	s_nop 0
	ds_read_b128 v[208:211], v22 offset:16128
	s_nop 0
	ds_read_b128 v[214:217], v22 offset:16192
	s_waitcnt lgkmcnt(13)
	v_mfma_f32_16x16x32_bf16 v[42:45], v[158:161], v[38:41], 0
	s_waitcnt lgkmcnt(12)
	v_mfma_f32_16x16x32_bf16 v[74:77], v[162:165], v[70:73], v[42:45]
	s_nop 5
	s_nop 0
	ds_read_b128 v[218:221], v22 offset:18432
	s_nop 0
	ds_read_b128 v[222:225], v22 offset:18496
	s_waitcnt lgkmcnt(13)
	v_mfma_f32_16x16x32_bf16 v[42:45], v[166:169], v[38:41], 0
	s_waitcnt lgkmcnt(12)
	v_mfma_f32_16x16x32_bf16 v[66:69], v[170:173], v[70:73], v[42:45]
	s_nop 5
	s_nop 0
	s_nop 0
	s_waitcnt lgkmcnt(11)
	v_mfma_f32_16x16x32_bf16 v[42:45], v[174:177], v[38:41], 0
	s_waitcnt lgkmcnt(10)
	v_mfma_f32_16x16x32_bf16 v[62:65], v[178:181], v[70:73], v[42:45]
	s_nop 5
	s_nop 0
	s_nop 0
	s_waitcnt lgkmcnt(9)
	v_mfma_f32_16x16x32_bf16 v[42:45], v[182:185], v[38:41], 0
	s_waitcnt lgkmcnt(8)
	v_mfma_f32_16x16x32_bf16 v[58:61], v[186:189], v[70:73], v[42:45]
	s_nop 5
	s_nop 0
	s_nop 0
	s_waitcnt lgkmcnt(7)
	v_mfma_f32_16x16x32_bf16 v[42:45], v[190:193], v[38:41], 0
	s_waitcnt lgkmcnt(6)
	v_mfma_f32_16x16x32_bf16 v[54:57], v[196:199], v[70:73], v[42:45]
	s_nop 5
	s_nop 0
	s_nop 0
	s_waitcnt lgkmcnt(5)
	v_mfma_f32_16x16x32_bf16 v[42:45], v[200:203], v[38:41], 0
	s_waitcnt lgkmcnt(4)
	v_mfma_f32_16x16x32_bf16 v[50:53], v[204:207], v[70:73], v[42:45]
	s_nop 5
	s_nop 0
	s_nop 0
	s_waitcnt lgkmcnt(3)
	v_mfma_f32_16x16x32_bf16 v[42:45], v[208:211], v[38:41], 0
	s_waitcnt lgkmcnt(2)
	v_mfma_f32_16x16x32_bf16 v[46:49], v[214:217], v[70:73], v[42:45]
	s_nop 5
	s_nop 0
	s_nop 0
	s_waitcnt lgkmcnt(1)
	v_mfma_f32_16x16x32_bf16 v[42:45], v[218:221], v[38:41], 0
	v_mfma_f32_16x16x32_bf16 v[38:41], v[10:13], v[38:41], 0
	s_waitcnt lgkmcnt(0)
	v_mfma_f32_16x16x32_bf16 v[42:45], v[222:225], v[70:73], v[42:45]
	v_mfma_f32_16x16x32_bf16 v[38:41], v[18:21], v[70:73], v[38:41]
	ds_read_b32 v128, v111 offset:512
	ds_read_b32 v129, v112 offset:512
	ds_read_b32 v130, v113 offset:512
	ds_read_b32 v131, v114 offset:512
	ds_read_b32 v132, v111 offset:436
	ds_read_b32 v133, v111 offset:384
	ds_read_b32 v134, v111 offset:380
	ds_read_b32 v135, v111 offset:376
	ds_read_b32 v136, v111 offset:372
	ds_read_b32 v137, v111 offset:320
	ds_read_b32 v138, v111 offset:316
	ds_read_b32 v139, v111 offset:312
	ds_read_b32 v140, v111 offset:308
	ds_read_b32 v141, v111 offset:256
	ds_read_b32 v142, v111 offset:252
	ds_read_b32 v143, v111 offset:248
	ds_read_b32 v144, v111 offset:244
	ds_read_b32 v145, v111 offset:192
	ds_read_b32 v146, v111 offset:188
	ds_read_b32 v147, v111 offset:184
	ds_read_b32 v148, v111 offset:180
	ds_read_b32 v149, v111 offset:128
	ds_read_b32 v150, v111 offset:124
	ds_read_b32 v151, v111 offset:120
	ds_read_b32 v152, v111 offset:116
	ds_read_b32 v153, v111 offset:64
	ds_read_b32 v154, v111 offset:60
	ds_read_b32 v155, v111 offset:56
	ds_read_b32 v156, v111 offset:52
	ds_read_b32 v157, v111
	ds_read_b32 v158, v115 offset:512
	ds_read_b32 v159, v116 offset:512
	ds_read_b32 v160, v117 offset:512
	ds_read_b32 v161, v111 offset:448
	ds_read_b32 v162, v111 offset:444
	ds_read_b32 v163, v111 offset:440
	s_waitcnt lgkmcnt(0)
	v_mov_b32_e32 v70, 0xf149f2ca
	v_mov_b32_e32 v73, 0xf149f2ca
	s_and_saveexec_b64 s[12:13], s[8:9]
	s_cbranch_execz .LBB0_325
	v_fmamk_f32 v73, v78, 0x3e000000, v128
.LBB0_325:
	s_or_b64 exec, exec, s[12:13]
	s_and_saveexec_b64 s[12:13], s[10:11]
	s_cbranch_execz .LBB0_327
	v_fmamk_f32 v70, v79, 0x3e000000, v129
.LBB0_327:
	s_or_b64 exec, exec, s[12:13]
	v_mov_b32_e32 v72, 0xf149f2ca
	v_mov_b32_e32 v78, 0xf149f2ca
	s_and_saveexec_b64 s[12:13], s[40:41]
	s_cbranch_execz .LBB0_329
	v_fmamk_f32 v78, v80, 0x3e000000, v130
.LBB0_329:
	s_or_b64 exec, exec, s[12:13]
	s_and_saveexec_b64 s[12:13], s[42:43]
	s_cbranch_execz .LBB0_331
	v_fmamk_f32 v72, v81, 0x3e000000, v131

; __device__ __forceinline__ void attn_unit(const Ptrs& P, int l, int b, int gk, int n, unsigned char* lds, int tid, bool dost) {
;     ...
;         for (int kt = 0; kt < 9; ++kt)
; #pragma unroll
;             for (int r = 0; r < 4; ++r) { const int dist = 128 + lc - 16 * kt - 4 * g - r; const int j = 16 * (qs + kt) + 4 * g + r;
;                 const bool valid = (dist >= 0) && (dist < 128) && (n >= 1) && (n >= 2 || j >= 128);
;                 const float lg = valid ? (st[kt][r] * 0.125f + hb[w * 128 + (dist & 127)]) : NEGV; st[kt][r] = lg; mx = fmaxf(mx, lg); }
.LBB0_335:
	v_fmamk_f32 v23, v77, 0x3e000000, v132
.LBB0_336:
	s_cmp_gt_u32 s19, 5
	s_cselect_b64 s[12:13], -1, 0
	s_or_b64 s[12:13], s[76:77], s[12:13]
	s_and_b64 s[12:13], s[84:85], s[12:13]
	v_mov_b32_e32 v26, 0xf149f2ca
	s_andn2_b64 vcc, exec, s[12:13]
	v_mov_b32_e32 v71, 0xf149f2ca
	s_cbranch_vccnz .LBB0_338
	v_fmamk_f32 v71, v66, 0x3e000000, v133
.LBB0_338:
	v_cndmask_b32_e64 v66, 0, 1, s[84:85]
	v_cmp_ne_u32_e64 s[38:39], 1, v66
	s_andn2_b64 vcc, exec, s[84:85]
	s_cbranch_vccnz .LBB0_341
	s_add_i32 s12, s20, 0xffffffa1
	s_cmp_gt_u32 s12, 0xffffff7f
	s_cselect_b64 s[12:13], -1, 0
	s_xor_b64 s[28:29], s[76:77], -1
	s_and_b64 s[12:13], s[28:29], s[12:13]
	v_mov_b32_e32 v26, 0xf149f2ca
	s_and_b64 vcc, exec, s[12:13]
	s_cbranch_vccnz .LBB0_341
	v_fmamk_f32 v26, v67, 0x3e000000, v134
.LBB0_341:
	v_mov_b32_e32 v66, 0xf149f2ca
	s_and_b64 vcc, exec, s[38:39]
	v_mov_b32_e32 v67, 0xf149f2ca
	s_cbranch_vccnz .LBB0_344
	s_add_i32 s12, s20, 0xffffffa2
	s_cmp_gt_u32 s12, 0xffffff7f
	s_cselect_b64 s[12:13], -1, 0
	s_xor_b64 s[28:29], s[76:77], -1
	s_and_b64 s[12:13], s[28:29], s[12:13]
	v_mov_b32_e32 v67, 0xf149f2ca
	s_and_b64 vcc, exec, s[12:13]
	s_cbranch_vccnz .LBB0_344
	v_fmamk_f32 v67, v68, 0x3e000000, v135
.LBB0_344:
	s_and_b64 vcc, exec, s[38:39]
	s_cbranch_vccnz .LBB0_347
	s_add_i32 s12, s20, 0xffffffa3
	s_cmp_gt_u32 s12, 0xffffff7f
	s_cselect_b64 s[12:13], -1, 0
	s_xor_b64 s[28:29], s[76:77], -1
	s_and_b64 s[12:13], s[28:29], s[12:13]
	v_mov_b32_e32 v66, 0xf149f2ca
	s_and_b64 vcc, exec, s[12:13]
	s_cbranch_vccnz .LBB0_347
	v_fmamk_f32 v66, v69, 0x3e000000, v136
.LBB0_347:
	s_cmp_gt_u32 s19, 4
	s_cselect_b64 s[12:13], -1, 0
	s_or_b64 s[12:13], s[76:77], s[12:13]
	s_and_b64 s[12:13], s[84:85], s[12:13]
	v_mov_b32_e32 v68, 0xf149f2ca
	s_andn2_b64 vcc, exec, s[12:13]
	v_mov_b32_e32 v69, 0xf149f2ca
	s_cbranch_vccnz .LBB0_349
	v_fmamk_f32 v69, v62, 0x3e000000, v137
.LBB0_349:
	s_and_b64 vcc, exec, s[38:39]
	s_cbranch_vccnz .LBB0_352
	s_add_i32 s12, s20, 0xffffffb1
	s_cmp_gt_u32 s12, 0xffffff7f
	s_cselect_b64 s[12:13], -1, 0
	s_xor_b64 s[28:29], s[76:77], -1
	s_and_b64 s[12:13], s[28:29], s[12:13]
	v_mov_b32_e32 v68, 0xf149f2ca
	s_and_b64 vcc, exec, s[12:13]
	s_cbranch_vccnz .LBB0_352
	v_fmamk_f32 v68, v63, 0x3e000000, v138
.LBB0_352:
	v_mov_b32_e32 v62, 0xf149f2ca
	s_and_b64 vcc, exec, s[38:39]
	v_mov_b32_e32 v63, 0xf149f2ca
	s_cbranch_vccnz .LBB0_355
	s_add_i32 s12, s20, 0xffffffb2
	s_cmp_gt_u32 s12, 0xffffff7f
	s_cselect_b64 s[12:13], -1, 0
	s_xor_b64 s[28:29], s[76:77], -1
	s_and_b64 s[12:13], s[28:29], s[12:13]
	v_mov_b32_e32 v63, 0xf149f2ca
	s_and_b64 vcc, exec, s[12:13]
	s_cbranch_vccnz .LBB0_355
	v_fmamk_f32 v63, v64, 0x3e000000, v139
.LBB0_355:
	s_and_b64 vcc, exec, s[38:39]
	s_cbranch_vccnz .LBB0_358
	s_add_i32 s12, s20, 0xffffffb3
	s_cmp_gt_u32 s12, 0xffffff7f
	s_cselect_b64 s[12:13], -1, 0
	s_xor_b64 s[28:29], s[76:77], -1
	s_and_b64 s[12:13], s[28:29], s[12:13]
	v_mov_b32_e32 v62, 0xf149f2ca
	s_and_b64 vcc, exec, s[12:13]
	s_cbranch_vccnz .LBB0_358
	v_fmamk_f32 v62, v65, 0x3e000000, v140
.LBB0_358:
	s_cmp_gt_u32 s19, 3
	s_cselect_b64 s[12:13], -1, 0
	s_or_b64 s[12:13], s[76:77], s[12:13]
	s_and_b64 s[12:13], s[84:85], s[12:13]
	v_mov_b32_e32 v64, 0xf149f2ca
	s_andn2_b64 vcc, exec, s[12:13]
	v_mov_b32_e32 v65, 0xf149f2ca
	s_cbranch_vccnz .LBB0_360
	v_fmamk_f32 v65, v58, 0x3e000000, v141
.LBB0_360:
	s_and_b64 vcc, exec, s[38:39]
	s_cbranch_vccnz .LBB0_363
	s_sub_i32 s12, s20, 63
	s_cmp_gt_u32 s12, 0xffffff7f
	s_cselect_b64 s[12:13], -1, 0
	s_xor_b64 s[28:29], s[76:77], -1
	s_and_b64 s[12:13], s[28:29], s[12:13]
	v_mov_b32_e32 v64, 0xf149f2ca
	s_and_b64 vcc, exec, s[12:13]
	s_cbranch_vccnz .LBB0_363
	v_fmamk_f32 v64, v59, 0x3e000000, v142
.LBB0_363:
	v_mov_b32_e32 v58, 0xf149f2ca
	s_and_b64 vcc, exec, s[38:39]
	v_mov_b32_e32 v59, 0xf149f2ca
	s_cbranch_vccnz .LBB0_366
	s_sub_i32 s12, s20, 62
	s_cmp_gt_u32 s12, 0xffffff7f
	s_cselect_b64 s[12:13], -1, 0
	s_xor_b64 s[28:29], s[76:77], -1
	s_and_b64 s[12:13], s[28:29], s[12:13]
	v_mov_b32_e32 v59, 0xf149f2ca
	s_and_b64 vcc, exec, s[12:13]
	s_cbranch_vccnz .LBB0_366
	v_fmamk_f32 v59, v60, 0x3e000000, v143
.LBB0_366:
	s_and_b64 vcc, exec, s[38:39]
	s_cbranch_vccnz .LBB0_369
	s_sub_i32 s12, s20, 61
	s_cmp_gt_u32 s12, 0xffffff7f
	s_cselect_b64 s[12:13], -1, 0
	s_xor_b64 s[28:29], s[76:77], -1
	s_and_b64 s[12:13], s[28:29], s[12:13]
	v_mov_b32_e32 v58, 0xf149f2ca
	s_and_b64 vcc, exec, s[12:13]
	s_cbranch_vccnz .LBB0_369
	v_fmamk_f32 v58, v61, 0x3e000000, v144
.LBB0_369:
	s_cmp_gt_u32 s19, 2
	s_cselect_b64 s[12:13], -1, 0
	s_or_b64 s[12:13], s[76:77], s[12:13]
	s_and_b64 s[12:13], s[84:85], s[12:13]
	v_mov_b32_e32 v60, 0xf149f2ca
	s_andn2_b64 vcc, exec, s[12:13]
	v_mov_b32_e32 v61, 0xf149f2ca
	s_cbranch_vccnz .LBB0_371
	v_fmamk_f32 v61, v54, 0x3e000000, v145
; __device__ __forceinline__ void attn_unit(const Ptrs& P, int l, int b, int gk, int n, unsigned char* lds, int tid, bool dost) {
;     ...
;         for (int kt = 0; kt < 9; ++kt)
; #pragma unroll
;             for (int r = 0; r < 4; ++r) { const int dist = 128 + lc - 16 * kt - 4 * g - r; const int j = 16 * (qs + kt) + 4 * g + r;
;                 const bool valid = (dist >= 0) && (dist < 128) && (n >= 1) && (n >= 2 || j >= 128);
;                 const float lg = valid ? (st[kt][r] * 0.125f + hb[w * 128 + (dist & 127)]) : NEGV; st[kt][r] = lg; mx = fmaxf(mx, lg); }
.LBB0_371:
	s_and_b64 vcc, exec, s[38:39]
	s_cbranch_vccnz .LBB0_374
	s_sub_i32 s12, s20, 47
	s_cmp_gt_u32 s12, 0xffffff7f
	s_cselect_b64 s[12:13], -1, 0
	s_xor_b64 s[28:29], s[76:77], -1
	s_and_b64 s[12:13], s[28:29], s[12:13]
	v_mov_b32_e32 v60, 0xf149f2ca
	s_and_b64 vcc, exec, s[12:13]
	s_cbranch_vccnz .LBB0_374
	v_fmamk_f32 v60, v55, 0x3e000000, v146
.LBB0_374:
	v_mov_b32_e32 v54, 0xf149f2ca
	s_and_b64 vcc, exec, s[38:39]
	v_mov_b32_e32 v55, 0xf149f2ca
	s_cbranch_vccnz .LBB0_377
	s_sub_i32 s12, s20, 46
	s_cmp_gt_u32 s12, 0xffffff7f
	s_cselect_b64 s[12:13], -1, 0
	s_xor_b64 s[28:29], s[76:77], -1
	s_and_b64 s[12:13], s[28:29], s[12:13]
	v_mov_b32_e32 v55, 0xf149f2ca
	s_and_b64 vcc, exec, s[12:13]
	s_cbranch_vccnz .LBB0_377
	v_fmamk_f32 v55, v56, 0x3e000000, v147
.LBB0_377:
	s_and_b64 vcc, exec, s[38:39]
	s_cbranch_vccnz .LBB0_380
	s_sub_i32 s12, s20, 45
	s_cmp_gt_u32 s12, 0xffffff7f
	s_cselect_b64 s[12:13], -1, 0
	s_xor_b64 s[28:29], s[76:77], -1
	s_and_b64 s[12:13], s[28:29], s[12:13]
	v_mov_b32_e32 v54, 0xf149f2ca
	s_and_b64 vcc, exec, s[12:13]
	s_cbranch_vccnz .LBB0_380
	v_fmamk_f32 v54, v57, 0x3e000000, v148
.LBB0_380:
	s_cmp_gt_u32 s19, 1
	s_cselect_b64 s[12:13], -1, 0
	s_or_b64 s[12:13], s[76:77], s[12:13]
	s_and_b64 s[12:13], s[84:85], s[12:13]
	v_mov_b32_e32 v56, 0xf149f2ca
	s_andn2_b64 vcc, exec, s[12:13]
	v_mov_b32_e32 v57, 0xf149f2ca
	s_cbranch_vccnz .LBB0_382
	v_fmamk_f32 v57, v50, 0x3e000000, v149
.LBB0_382:
	s_and_b64 vcc, exec, s[38:39]
	s_cbranch_vccnz .LBB0_385
	s_sub_i32 s12, s20, 31
	s_cmp_gt_u32 s12, 0xffffff7f
	s_cselect_b64 s[12:13], -1, 0
	s_xor_b64 s[28:29], s[76:77], -1
	s_and_b64 s[12:13], s[28:29], s[12:13]
	v_mov_b32_e32 v56, 0xf149f2ca
	s_and_b64 vcc, exec, s[12:13]
	s_cbranch_vccnz .LBB0_385
	v_fmamk_f32 v56, v51, 0x3e000000, v150
.LBB0_385:
	v_mov_b32_e32 v50, 0xf149f2ca
	s_and_b64 vcc, exec, s[38:39]
	v_mov_b32_e32 v51, 0xf149f2ca
	s_cbranch_vccnz .LBB0_388
	s_sub_i32 s12, s20, 30
	s_cmp_gt_u32 s12, 0xffffff7f
	s_cselect_b64 s[12:13], -1, 0
	s_xor_b64 s[28:29], s[76:77], -1
	s_and_b64 s[12:13], s[28:29], s[12:13]
	v_mov_b32_e32 v51, 0xf149f2ca
	s_and_b64 vcc, exec, s[12:13]
	s_cbranch_vccnz .LBB0_388
	v_fmamk_f32 v51, v52, 0x3e000000, v151
.LBB0_388:
	s_and_b64 vcc, exec, s[38:39]
	s_cbranch_vccnz .LBB0_391
	s_sub_i32 s12, s20, 29
	s_cmp_gt_u32 s12, 0xffffff7f
	s_cselect_b64 s[12:13], -1, 0
	s_xor_b64 s[28:29], s[76:77], -1
	s_and_b64 s[12:13], s[28:29], s[12:13]
	v_mov_b32_e32 v50, 0xf149f2ca
	s_and_b64 vcc, exec, s[12:13]
	s_cbranch_vccnz .LBB0_391
	v_fmamk_f32 v50, v53, 0x3e000000, v152
.LBB0_391:
	s_cmp_lg_u32 s20, 0
	s_cselect_b64 s[12:13], -1, 0
	s_or_b64 s[12:13], s[76:77], s[12:13]
	s_and_b64 s[12:13], s[84:85], s[12:13]
	v_mov_b32_e32 v52, 0xf149f2ca
	s_andn2_b64 vcc, exec, s[12:13]
	v_mov_b32_e32 v53, 0xf149f2ca
	s_cbranch_vccnz .LBB0_393
	v_fmamk_f32 v53, v46, 0x3e000000, v153
.LBB0_393:
	s_and_b64 vcc, exec, s[38:39]
	s_cbranch_vccnz .LBB0_396
	s_add_i32 s12, s20, -15
	s_cmp_gt_u32 s12, 0xffffff7f
	s_cselect_b64 s[12:13], -1, 0
	s_xor_b64 s[28:29], s[76:77], -1
	s_and_b64 s[12:13], s[28:29], s[12:13]
	v_mov_b32_e32 v52, 0xf149f2ca
	s_and_b64 vcc, exec, s[12:13]
	s_cbranch_vccnz .LBB0_396
	v_fmamk_f32 v52, v47, 0x3e000000, v154
.LBB0_396:
	v_mov_b32_e32 v47, 0xf149f2ca
	s_and_b64 vcc, exec, s[38:39]
	v_mov_b32_e32 v74, 0xf149f2ca
	s_cbranch_vccnz .LBB0_399
	s_add_i32 s12, s20, -14
	s_cmp_gt_u32 s12, 0xffffff7f
	s_cselect_b64 s[12:13], -1, 0
	s_xor_b64 s[28:29], s[76:77], -1
	s_and_b64 s[12:13], s[28:29], s[12:13]
	v_mov_b32_e32 v74, 0xf149f2ca
	s_and_b64 vcc, exec, s[12:13]
	s_cbranch_vccnz .LBB0_399
	v_fmamk_f32 v74, v48, 0x3e000000, v155
.LBB0_399:
	s_and_b64 vcc, exec, s[38:39]
	s_cbranch_vccnz .LBB0_402
	s_add_i32 s20, s20, -13
	s_cmp_gt_u32 s20, 0xffffff7f
	s_cselect_b64 s[12:13], -1, 0
	s_xor_b64 s[20:21], s[76:77], -1
	s_and_b64 s[12:13], s[20:21], s[12:13]
	v_mov_b32_e32 v47, 0xf149f2ca
	s_and_b64 vcc, exec, s[12:13]
	s_cbranch_vccnz .LBB0_402
	v_fmamk_f32 v47, v49, 0x3e000000, v156
.LBB0_402:
	v_mov_b32_e32 v48, 0xf149f2ca
	v_mov_b32_e32 v49, 0xf149f2ca
	s_and_saveexec_b64 s[12:13], s[46:47]
	s_cbranch_execz .LBB0_404
	v_fmamk_f32 v49, v42, 0x3e000000, v157
.LBB0_404:
	s_or_b64 exec, exec, s[12:13]
	s_and_saveexec_b64 s[12:13], s[4:5]
	s_cbranch_execz .LBB0_406
	v_fmamk_f32 v48, v43, 0x3e000000, v158
.LBB0_406:
	s_or_b64 exec, exec, s[12:13]
	v_mov_b32_e32 v42, 0xf149f2ca
	v_mov_b32_e32 v43, 0xf149f2ca
	s_and_saveexec_b64 s[12:13], s[6:7]
	s_cbranch_execz .LBB0_408
	v_fmamk_f32 v43, v44, 0x3e000000, v159
.LBB0_408:
	s_or_b64 exec, exec, s[12:13]
	s_and_saveexec_b64 s[12:13], s[44:45]
	s_cbranch_execz .LBB0_410
	v_fmamk_f32 v42, v45, 0x3e000000, v160

; __device__ __forceinline__ void attn_unit(const Ptrs& P, int l, int b, int gk, int n, unsigned char* lds, int tid, bool dost) {
;     ...
;         for (int kt = 0; kt < 9; ++kt)
; #pragma unroll
;             for (int r = 0; r < 4; ++r) { const int dist = 128 + lc - 16 * kt - 4 * g - r; const int j = 16 * (qs + kt) + 4 * g + r;
;                 const bool valid = (dist >= 0) && (dist < 128) && (n >= 1) && (n >= 2 || j >= 128);
;                 const float lg = valid ? (st[kt][r] * 0.125f + hb[w * 128 + (dist & 127)]) : NEGV; st[kt][r] = lg; mx = fmaxf(mx, lg); }
.LBB0_426:
	v_fmamk_f32 v79, v74, 0x3e000000, v161
	s_and_b64 vcc, exec, s[38:39]
	s_cbranch_vccnz .LBB0_333
.LBB0_427:
	v_fmamk_f32 v22, v75, 0x3e000000, v162
	v_mov_b32_e32 v23, 0xf149f2ca
	s_and_b64 vcc, exec, s[38:39]
	v_mov_b32_e32 v27, 0xf149f2ca
	s_cbranch_vccnz .LBB0_334
.LBB0_428:
	v_fmamk_f32 v27, v76, 0x3e000000, v163
	s_and_b64 vcc, exec, s[38:39]
	s_cbranch_vccz .LBB0_335
	s_branch .LBB0_336
